# v33 + conv: s_waitcnt vmcnt(0) after the normalize loop (drain the tile's output stores before the next tile's loads are issued)
# speedup vs baseline: 1.0092x; 1.0066x over previous
; __device__ __forceinline__ float sigm(float x) { return __builtin_amdgcn_rcpf(1.0f + __builtin_amdgcn_exp2f(-LOG2E * x)); }
; __device__ __forceinline__ unsigned pk2(float lo, float hi) { return pg8::cvt_pk_bf16(lo, hi); }
; __device__ __forceinline__ void conv_phase(LAS unsigned char* lds, const bf16* U, const float* state, const float* wdw, const float* bdw, const float* lng, const float* lnb, bf16* Z, int blk, int nblk, int tid) {
;     ...
; #pragma unroll 8
;         for (int t = 0; t < 8 * ng; ++t) { const f32x2 st = stat[t]; const unsigned v = tile[t * 512 + tid]; const float y0 = __uint_as_float(v << 16), y1 = __uint_as_float(v & 0xffff0000u);
;             const float a0 = (y0 - st[0]) * st[1] * gg[0] + bb[0], a1 = (y1 - st[0]) * st[1] * gg[1] + bb[1];
;             *(unsigned*)(Z + (size_t)(t0 + t) * 1024 + c0) = pk2(a0 * pg8::sigm(a0), a1 * pg8::sigm(a1)); }
;         __syncthreads();
.Lconv_norm:
	ds_read_b128 v[62:65], v229
	ds_read_b64 v[242:243], v228
	s_waitcnt lgkmcnt(0)
	v_lshlrev_b32_e32 v81, 16, v62
	v_and_b32_e32 v82, 0xffff0000, v62
	v_lshlrev_b32_e32 v248, 16, v63
	v_and_b32_e32 v249, 0xffff0000, v63
	v_sub_f32_e32 v81, v81, v242
	v_sub_f32_e32 v82, v82, v242
	v_sub_f32_e32 v248, v248, v242
	v_sub_f32_e32 v249, v249, v242
	v_mul_f32_e32 v81, v243, v81
	v_mul_f32_e32 v82, v243, v82
	v_mul_f32_e32 v248, v243, v248
	v_mul_f32_e32 v249, v243, v249
	v_fma_f32 v81, v210, v81, v218
	v_fma_f32 v82, v211, v82, v219
	v_fma_f32 v248, v212, v248, v220
	v_fma_f32 v249, v213, v249, v221
	v_mul_f32_e32 v236, 0xbfb8aa3b, v81
	v_mul_f32_e32 v237, 0xbfb8aa3b, v82
	v_mul_f32_e32 v62, 0xbfb8aa3b, v248
	v_mul_f32_e32 v63, 0xbfb8aa3b, v249
	v_exp_f32_e32 v236, v236
	v_exp_f32_e32 v237, v237
	v_exp_f32_e32 v62, v62
	v_exp_f32_e32 v63, v63
	s_nop 0
	v_add_f32_e32 v236, 1.0, v236
	v_add_f32_e32 v237, 1.0, v237
	v_add_f32_e32 v62, 1.0, v62
	v_add_f32_e32 v63, 1.0, v63
	v_rcp_f32_e32 v236, v236
	v_rcp_f32_e32 v237, v237
	v_rcp_f32_e32 v62, v62
	v_rcp_f32_e32 v63, v63
	s_nop 0
	v_mul_f32_e32 v81, v81, v236
	v_mul_f32_e32 v82, v82, v237
	v_mul_f32_e32 v248, v248, v62
	v_mul_f32_e32 v249, v249, v63
	v_cvt_pk_bf16_f32 v244, v81, v82
	v_cvt_pk_bf16_f32 v245, v248, v249
	v_lshlrev_b32_e32 v81, 16, v64
	v_and_b32_e32 v82, 0xffff0000, v64
	v_lshlrev_b32_e32 v248, 16, v65
	v_and_b32_e32 v249, 0xffff0000, v65
	v_sub_f32_e32 v81, v81, v242
	v_sub_f32_e32 v82, v82, v242
	v_sub_f32_e32 v248, v248, v242
	v_sub_f32_e32 v249, v249, v242
	v_mul_f32_e32 v81, v243, v81
	v_mul_f32_e32 v82, v243, v82
	v_mul_f32_e32 v248, v243, v248
	v_mul_f32_e32 v249, v243, v249
	v_fma_f32 v81, v214, v81, v222
	v_fma_f32 v82, v215, v82, v223
	v_fma_f32 v248, v216, v248, v224
	v_fma_f32 v249, v217, v249, v225
	v_mul_f32_e32 v236, 0xbfb8aa3b, v81
	v_mul_f32_e32 v237, 0xbfb8aa3b, v82
	v_mul_f32_e32 v64, 0xbfb8aa3b, v248
	v_mul_f32_e32 v65, 0xbfb8aa3b, v249
	v_exp_f32_e32 v236, v236
	v_exp_f32_e32 v237, v237
	v_exp_f32_e32 v64, v64
	v_exp_f32_e32 v65, v65
	s_nop 0
	v_add_f32_e32 v236, 1.0, v236
	v_add_f32_e32 v237, 1.0, v237
	v_add_f32_e32 v64, 1.0, v64
	v_add_f32_e32 v65, 1.0, v65
	v_rcp_f32_e32 v236, v236
	v_rcp_f32_e32 v237, v237
	v_rcp_f32_e32 v64, v64
	v_rcp_f32_e32 v65, v65
	s_nop 0
	v_mul_f32_e32 v81, v81, v236
	v_mul_f32_e32 v82, v82, v237
	v_mul_f32_e32 v248, v248, v64
	v_mul_f32_e32 v249, v249, v65
	v_cvt_pk_bf16_f32 v246, v81, v82
	v_cvt_pk_bf16_f32 v247, v248, v249
	global_store_dwordx4 v[226:227], v[244:247], off
	v_add_u32_e32 v229, 0x2000, v229
	v_add_u32_e32 v228, 32, v228
	v_lshl_add_u64 v[226:227], v[226:227], 0, s[4:5]
	s_add_i32 s1, s1, 32
	s_cmp_lt_u32 s1, s0
	s_cbranch_scc1 .Lconv_norm
	s_waitcnt vmcnt(0)
	s_add_i32 s14, s14, s98
	s_cmpk_gt_i32 s14, 0x43f
	s_barrier
	s_cbranch_scc0 .LBB0_79
